# main GEMM K-loop: one static s_setprio 1 for waves 4-7, per-segment priority flips removed
# baseline (speedup 1.0000x reference)
.LBB0_19:
	s_setprio 0
	s_cmp_gt_u32 s0, 12
	s_cselect_b64 s[64:65], -1, 0
	s_cmp_lt_u32 s0, 13
	s_cselect_b64 s[4:5], -1, 0
	v_writelane_b32 v251, s4, 57
	s_waitcnt lgkmcnt(0)
	v_add_co_u32_e64 v0, s[6:7], s0, -1
	v_writelane_b32 v251, s5, 58
	v_writelane_b32 v251, s0, 59
	s_add_i32 s0, s0, -13
	v_readfirstlane_b32 s1, v0
	s_cmp_lt_u32 s1, 12
	s_cselect_b32 s4, s1, s0
	s_and_b64 s[0:1], s[6:7], exec
	s_mov_b32 s0, s4
	v_writelane_b32 v251, s0, 60
	s_nop 1
	v_writelane_b32 v251, s1, 61
	s_cselect_b32 s0, s4, -1
	s_cmp_lg_u32 s0, 11
	v_writelane_b32 v251, s0, 62
	s_cselect_b64 s[0:1], -1, 0
	s_or_b64 s[0:1], s[0:1], s[64:65]
	s_and_b64 s[0:1], s[6:7], s[0:1]
	s_and_b64 vcc, exec, s[0:1]
	s_cbranch_vccnz .LBB0_104
	v_readlane_b32 s4, v252, 2
	v_readlane_b32 s0, v252, 0
	v_readlane_b32 s5, v252, 3
	v_mov_b32_e32 v0, v162
	v_readlane_b32 s1, v252, 1
	s_andn2_b64 vcc, exec, s[4:5]
	s_cbranch_vccnz .LBB0_104
	s_load_dwordx2 s[4:5], s[0:1], 0x158
	s_waitcnt vmcnt(0)
	v_ashrrev_i32_e32 v2, 5, v0
	v_and_b32_e32 v4, 31, v0
	v_ashrrev_i32_e32 v16, 3, v0
	v_lshlrev_b32_e32 v0, 3, v0
	s_waitcnt lgkmcnt(0)
	s_add_u32 s36, s4, 0x100000
	s_addc_u32 s37, s5, 0
	s_and_b64 s[4:5], s[6:7], exec
	s_cselect_b32 s72, 0x10000, 0
	s_mov_b64 s[8:9], s[72:73]
	s_cselect_b32 s72, 0x8000, 0
	s_mov_b64 s[10:11], s[72:73]
	s_cselect_b32 s72, 0x100000, 0
	v_and_b32_e32 v0, 56, v0
	s_mov_b64 s[12:13], s[72:73]
	s_cselect_b32 s72, 0x40000, 0
	v_mul_u32_u24_e32 v3, 0x84, v0
	v_lshlrev_b32_e32 v5, 2, v16
	v_readlane_b32 s5, v252, 7
	s_movk_i32 s4, 0x84
	s_mov_b64 s[14:15], s[72:73]
	s_cselect_b32 s72, 0x2c0000, 0
	v_add3_u32 v17, s5, v3, v5
	v_mul_lo_u32 v5, v2, s4
	v_lshlrev_b32_e32 v6, 2, v4
	s_mov_b64 s[16:17], s[72:73]
	s_cselect_b32 s72, 0x7c0000, 0
	v_add_u32_e32 v19, 8, v16
	v_add_u32_e32 v21, 24, v16
	v_add3_u32 v23, v5, v6, s5
	v_readlane_b32 s4, v251, 49
	s_cselect_b32 s38, 8, 0
	s_cselect_b32 s39, 0x400, 0
	s_cselect_b32 s40, 3, 0
	s_mov_b64 s[18:19], s[72:73]
	v_and_b32_e32 v18, 15, v16
	v_and_b32_e32 v20, 15, v19
	v_and_b32_e32 v22, 15, v21
	v_ashrrev_i32_e32 v3, 31, v2
	v_lshlrev_b32_e32 v4, 2, v4
	v_mov_b32_e32 v5, v1
	v_lshlrev_b32_e32 v0, 1, v0
	s_mov_b32 s41, s4
	v_readlane_b32 s5, v251, 50
	s_branch .LBB0_23

.LBB0_743:
	s_add_u32 s8, s8, 0x80
	s_addc_u32 s9, s9, 0
	s_add_u32 s27, s34, 0x100
	v_mov_b32_e32 v2, 0
	s_addc_u32 s34, s35, 0
	s_mov_b32 s10, 0
	v_mov_b32_e32 v3, v2
	v_mov_b32_e32 v4, v2
	v_mov_b32_e32 v5, v2
	v_mov_b32_e32 v6, v2
	v_mov_b32_e32 v7, v2
	v_mov_b32_e32 v8, v2
	v_mov_b32_e32 v9, v2
	v_mov_b32_e32 v18, v2
	v_mov_b32_e32 v19, v2
	v_mov_b32_e32 v20, v2
	v_mov_b32_e32 v21, v2
	v_mov_b32_e32 v22, v2
	v_mov_b32_e32 v23, v2
	v_mov_b32_e32 v24, v2
	v_mov_b32_e32 v25, v2
	v_mov_b32_e32 v34, v2
	v_mov_b32_e32 v35, v2
	v_mov_b32_e32 v36, v2
	v_mov_b32_e32 v37, v2
	v_mov_b32_e32 v38, v2
	v_mov_b32_e32 v39, v2
	v_mov_b32_e32 v40, v2
	v_mov_b32_e32 v41, v2
	v_mov_b32_e32 v50, v2
	v_mov_b32_e32 v51, v2
	v_mov_b32_e32 v52, v2
	v_mov_b32_e32 v53, v2
	v_mov_b32_e32 v54, v2
	v_mov_b32_e32 v55, v2
	v_mov_b32_e32 v56, v2
	v_mov_b32_e32 v57, v2
	v_mov_b32_e32 v10, v2
	v_mov_b32_e32 v11, v2
	v_mov_b32_e32 v12, v2
	v_mov_b32_e32 v13, v2
	v_mov_b32_e32 v14, v2
	v_mov_b32_e32 v15, v2
	v_mov_b32_e32 v16, v2
	v_mov_b32_e32 v17, v2
	v_mov_b32_e32 v26, v2
	v_mov_b32_e32 v27, v2
	v_mov_b32_e32 v28, v2
	v_mov_b32_e32 v29, v2
	v_mov_b32_e32 v30, v2
	v_mov_b32_e32 v31, v2
	v_mov_b32_e32 v32, v2
	v_mov_b32_e32 v33, v2
	v_mov_b32_e32 v42, v2
	v_mov_b32_e32 v43, v2
	v_mov_b32_e32 v44, v2
	v_mov_b32_e32 v45, v2
	v_mov_b32_e32 v46, v2
	v_mov_b32_e32 v47, v2
	v_mov_b32_e32 v48, v2
	v_mov_b32_e32 v49, v2
	v_mov_b32_e32 v58, v2
	v_mov_b32_e32 v59, v2
	v_mov_b32_e32 v60, v2
	v_mov_b32_e32 v61, v2
	v_mov_b32_e32 v62, v2
	v_mov_b32_e32 v63, v2
	v_mov_b32_e32 v64, v2
	v_mov_b32_e32 v65, v2
	v_mov_b32_e32 v66, v2
	v_mov_b32_e32 v67, v2
	v_mov_b32_e32 v68, v2
	v_mov_b32_e32 v69, v2
	v_mov_b32_e32 v70, v2
	v_mov_b32_e32 v71, v2
	v_mov_b32_e32 v72, v2
	v_mov_b32_e32 v73, v2
	v_mov_b32_e32 v82, v2
	v_mov_b32_e32 v83, v2
	v_mov_b32_e32 v84, v2
	v_mov_b32_e32 v85, v2
	v_mov_b32_e32 v86, v2
	v_mov_b32_e32 v87, v2
	v_mov_b32_e32 v88, v2
	v_mov_b32_e32 v89, v2
	v_mov_b32_e32 v98, v2
	v_mov_b32_e32 v99, v2
	v_mov_b32_e32 v100, v2
	v_mov_b32_e32 v101, v2
	v_mov_b32_e32 v102, v2
	v_mov_b32_e32 v103, v2
	v_mov_b32_e32 v104, v2
	v_mov_b32_e32 v105, v2
	v_mov_b32_e32 v114, v2
	v_mov_b32_e32 v115, v2
	v_mov_b32_e32 v116, v2
	v_mov_b32_e32 v117, v2
	v_mov_b32_e32 v118, v2
	v_mov_b32_e32 v119, v2
	v_mov_b32_e32 v120, v2
	v_mov_b32_e32 v121, v2
	v_mov_b32_e32 v74, v2
	v_mov_b32_e32 v75, v2
	v_mov_b32_e32 v76, v2
	v_mov_b32_e32 v77, v2
	v_mov_b32_e32 v78, v2
	v_mov_b32_e32 v79, v2
	v_mov_b32_e32 v80, v2
	v_mov_b32_e32 v81, v2
	v_mov_b32_e32 v90, v2
	v_mov_b32_e32 v91, v2
	v_mov_b32_e32 v92, v2
	v_mov_b32_e32 v93, v2
	v_mov_b32_e32 v94, v2
	v_mov_b32_e32 v95, v2
	v_mov_b32_e32 v96, v2
	v_mov_b32_e32 v97, v2
	v_mov_b32_e32 v106, v2
	v_mov_b32_e32 v107, v2
	v_mov_b32_e32 v108, v2
	v_mov_b32_e32 v109, v2
	v_mov_b32_e32 v110, v2
	v_mov_b32_e32 v111, v2
	v_mov_b32_e32 v112, v2
	v_mov_b32_e32 v113, v2
	v_mov_b32_e32 v122, v2
	v_mov_b32_e32 v123, v2
	v_mov_b32_e32 v124, v2
	v_mov_b32_e32 v125, v2
	v_mov_b32_e32 v126, v2
	v_mov_b32_e32 v127, v2
	v_mov_b32_e32 v128, v2
	v_mov_b32_e32 v129, v2
	v_readlane_b32 s98, v252, 60
	s_nop 3
	s_cmp_ge_u32 s98, 32
	s_cbranch_scc0 .Lgp_prio_done
	s_setprio 1
.Lgp_prio_done:
.LBB0_744:
	s_add_i32 s35, s10, 2
	s_add_u32 s37, s8, 0x80
	s_addc_u32 s11, s9, 0
	s_add_i32 s72, 0, 0x10000
	s_cmp_eq_u32 s65, s10
	s_cselect_b32 s11, s29, s11
	s_cselect_b32 s10, s28, s37
	v_add_u32_e32 v160, s72, v183
	s_cselect_b32 s81, s31, s34
	s_cselect_b32 s80, s30, s27
	s_add_i32 s37, 0, 0x14000
	ds_read_b128 v[130:133], v160
	ds_read_b128 v[134:137], v160 offset:1024
	ds_read_b128 v[156:159], v160 offset:2048
	ds_read_b128 v[186:189], v160 offset:3072
	v_add_u32_e32 v160, s37, v183
	ds_read_b128 v[190:193], v160
	ds_read_b128 v[194:197], v160 offset:1024
	ds_read_b128 v[198:201], v160 offset:2048
	ds_read_b128 v[202:205], v160 offset:3072
	v_lshl_add_u64 v[160:161], s[8:9], 0, v[150:151]
	s_add_i32 m0, s45, 0xc000
	ds_read_b128 v[206:209], v185
	ds_read_b128 v[210:213], v185 offset:1024
	ds_read_b128 v[214:217], v185 offset:2048
	ds_read_b128 v[218:221], v185 offset:3072
	ds_read_b128 v[222:225], v185 offset:4096
	ds_read_b128 v[226:229], v185 offset:5120
	ds_read_b128 v[230:233], v185 offset:6144
	ds_read_b128 v[234:237], v185 offset:7168
	global_load_lds_dwordx4 v[160:161], off
	v_lshl_add_u64 v[160:161], s[8:9], 0, v[152:153]
	s_add_i32 m0, s45, 0xe000
	s_nop 0
	global_load_lds_dwordx4 v[160:161], off
	s_waitcnt vmcnt(8)
	s_waitcnt lgkmcnt(0)
	s_barrier
	s_waitcnt lgkmcnt(0)
	v_mfma_f32_16x16x32_bf16 v[126:129], v[130:133], v[206:209], v[126:129]
	v_mfma_f32_16x16x32_bf16 v[122:125], v[156:159], v[206:209], v[122:125]
	v_mfma_f32_16x16x32_bf16 v[110:113], v[130:133], v[214:217], v[110:113]
	v_mfma_f32_16x16x32_bf16 v[106:109], v[156:159], v[214:217], v[106:109]
	v_mfma_f32_16x16x32_bf16 v[94:97], v[130:133], v[222:225], v[94:97]
	v_mfma_f32_16x16x32_bf16 v[90:93], v[156:159], v[222:225], v[90:93]
	v_mfma_f32_16x16x32_bf16 v[78:81], v[130:133], v[230:233], v[78:81]
	v_mfma_f32_16x16x32_bf16 v[74:77], v[156:159], v[230:233], v[74:77]
	v_mfma_f32_16x16x32_bf16 v[126:129], v[134:137], v[210:213], v[126:129]
	v_mfma_f32_16x16x32_bf16 v[122:125], v[186:189], v[210:213], v[122:125]
	v_mfma_f32_16x16x32_bf16 v[110:113], v[134:137], v[218:221], v[110:113]
	v_mfma_f32_16x16x32_bf16 v[106:109], v[186:189], v[218:221], v[106:109]
	v_mfma_f32_16x16x32_bf16 v[94:97], v[134:137], v[226:229], v[94:97]
	v_mfma_f32_16x16x32_bf16 v[90:93], v[186:189], v[226:229], v[90:93]
	v_mfma_f32_16x16x32_bf16 v[78:81], v[134:137], v[234:237], v[78:81]
	v_mfma_f32_16x16x32_bf16 v[74:77], v[186:189], v[234:237], v[74:77]
	v_mfma_f32_16x16x32_bf16 v[118:121], v[190:193], v[206:209], v[118:121]
	v_mfma_f32_16x16x32_bf16 v[114:117], v[198:201], v[206:209], v[114:117]
	v_mfma_f32_16x16x32_bf16 v[102:105], v[190:193], v[214:217], v[102:105]
	v_mfma_f32_16x16x32_bf16 v[98:101], v[198:201], v[214:217], v[98:101]
	v_mfma_f32_16x16x32_bf16 v[86:89], v[190:193], v[222:225], v[86:89]
	v_mfma_f32_16x16x32_bf16 v[82:85], v[198:201], v[222:225], v[82:85]
	v_mfma_f32_16x16x32_bf16 v[70:73], v[190:193], v[230:233], v[70:73]
	v_mfma_f32_16x16x32_bf16 v[66:69], v[198:201], v[230:233], v[66:69]
	v_mfma_f32_16x16x32_bf16 v[118:121], v[194:197], v[210:213], v[118:121]
	v_mfma_f32_16x16x32_bf16 v[114:117], v[202:205], v[210:213], v[114:117]
	v_mfma_f32_16x16x32_bf16 v[102:105], v[194:197], v[218:221], v[102:105]
	v_mfma_f32_16x16x32_bf16 v[98:101], v[202:205], v[218:221], v[98:101]
	v_mfma_f32_16x16x32_bf16 v[86:89], v[194:197], v[226:229], v[86:89]
	v_mfma_f32_16x16x32_bf16 v[82:85], v[202:205], v[226:229], v[82:85]
	v_mfma_f32_16x16x32_bf16 v[70:73], v[194:197], v[234:237], v[70:73]
	v_mfma_f32_16x16x32_bf16 v[66:69], v[202:205], v[234:237], v[66:69]
	s_barrier
	s_add_i32 s72, s72, s33
	v_lshl_add_u64 v[160:161], s[80:81], 0, v[0:1]
	s_mov_b32 m0, s72
	ds_read_b128 v[206:209], v185 offset:16384
	ds_read_b128 v[210:213], v185 offset:17408
	ds_read_b128 v[214:217], v185 offset:18432
	ds_read_b128 v[218:221], v185 offset:19456
	ds_read_b128 v[222:225], v185 offset:20480
	ds_read_b128 v[226:229], v185 offset:21504
	ds_read_b128 v[230:233], v185 offset:22528
	ds_read_b128 v[234:237], v185 offset:23552
	global_load_lds_dwordx4 v[160:161], off
	s_add_i32 m0, s72, 0x2000
	v_lshl_add_u64 v[238:239], s[80:81], 0, v[144:145]
	s_add_u32 s80, s80, s39
	s_addc_u32 s81, s81, 0
	s_add_i32 s37, s37, s33
	global_load_lds_dwordx4 v[238:239], off
	v_lshl_add_u64 v[240:241], s[80:81], 0, v[0:1]
	s_mov_b32 m0, s37
	v_lshl_add_u64 v[242:243], s[80:81], 0, v[144:145]
	global_load_lds_dwordx4 v[240:241], off
	s_add_i32 m0, s37, 0x2000
	v_lshl_add_u64 v[244:245], s[10:11], 0, v[146:147]
	global_load_lds_dwordx4 v[242:243], off
	s_mov_b32 m0, s45
	v_lshl_add_u64 v[246:247], s[10:11], 0, v[142:143]
	global_load_lds_dwordx4 v[244:245], off
	s_mov_b32 m0, s59
	s_nop 0
	global_load_lds_dwordx4 v[246:247], off
	s_waitcnt vmcnt(8)
	s_waitcnt lgkmcnt(0)
	s_barrier
	s_waitcnt lgkmcnt(0)
	v_mfma_f32_16x16x32_bf16 v[62:65], v[130:133], v[206:209], v[62:65]
	v_mfma_f32_16x16x32_bf16 v[58:61], v[156:159], v[206:209], v[58:61]
	v_mfma_f32_16x16x32_bf16 v[46:49], v[130:133], v[214:217], v[46:49]
	v_mfma_f32_16x16x32_bf16 v[42:45], v[156:159], v[214:217], v[42:45]
	v_mfma_f32_16x16x32_bf16 v[30:33], v[130:133], v[222:225], v[30:33]
	v_mfma_f32_16x16x32_bf16 v[26:29], v[156:159], v[222:225], v[26:29]
	v_mfma_f32_16x16x32_bf16 v[14:17], v[130:133], v[230:233], v[14:17]
	v_mfma_f32_16x16x32_bf16 v[10:13], v[156:159], v[230:233], v[10:13]
	v_mfma_f32_16x16x32_bf16 v[62:65], v[134:137], v[210:213], v[62:65]
	v_mfma_f32_16x16x32_bf16 v[58:61], v[186:189], v[210:213], v[58:61]
	v_mfma_f32_16x16x32_bf16 v[46:49], v[134:137], v[218:221], v[46:49]
	v_mfma_f32_16x16x32_bf16 v[42:45], v[186:189], v[218:221], v[42:45]
	v_mfma_f32_16x16x32_bf16 v[30:33], v[134:137], v[226:229], v[30:33]
	v_mfma_f32_16x16x32_bf16 v[26:29], v[186:189], v[226:229], v[26:29]
	v_mfma_f32_16x16x32_bf16 v[14:17], v[134:137], v[234:237], v[14:17]
	v_mfma_f32_16x16x32_bf16 v[10:13], v[186:189], v[234:237], v[10:13]
	v_mfma_f32_16x16x32_bf16 v[54:57], v[190:193], v[206:209], v[54:57]
	v_mfma_f32_16x16x32_bf16 v[50:53], v[198:201], v[206:209], v[50:53]
	v_mfma_f32_16x16x32_bf16 v[38:41], v[190:193], v[214:217], v[38:41]
	v_mfma_f32_16x16x32_bf16 v[34:37], v[198:201], v[214:217], v[34:37]
	v_mfma_f32_16x16x32_bf16 v[22:25], v[190:193], v[222:225], v[22:25]
	v_mfma_f32_16x16x32_bf16 v[18:21], v[198:201], v[222:225], v[18:21]
	v_mfma_f32_16x16x32_bf16 v[6:9], v[190:193], v[230:233], v[6:9]
	v_mfma_f32_16x16x32_bf16 v[2:5], v[198:201], v[230:233], v[2:5]
	v_mfma_f32_16x16x32_bf16 v[54:57], v[194:197], v[210:213], v[54:57]
	v_mfma_f32_16x16x32_bf16 v[50:53], v[202:205], v[210:213], v[50:53]
	v_mfma_f32_16x16x32_bf16 v[38:41], v[194:197], v[218:221], v[38:41]
	v_mfma_f32_16x16x32_bf16 v[34:37], v[202:205], v[218:221], v[34:37]
	v_mfma_f32_16x16x32_bf16 v[22:25], v[194:197], v[226:229], v[22:25]
	v_mfma_f32_16x16x32_bf16 v[18:21], v[202:205], v[226:229], v[18:21]
	v_mfma_f32_16x16x32_bf16 v[6:9], v[194:197], v[234:237], v[6:9]
	v_mfma_f32_16x16x32_bf16 v[2:5], v[202:205], v[234:237], v[2:5]
	s_barrier
	s_add_i32 s37, 0, 0x1c000
	v_add_u32_e32 v186, s66, v183
	v_add_u32_e32 v202, s37, v183
	ds_read_b128 v[130:133], v186
	ds_read_b128 v[134:137], v186 offset:1024
	ds_read_b128 v[156:159], v186 offset:2048
	ds_read_b128 v[186:189], v186 offset:3072
	ds_read_b128 v[190:193], v202
	ds_read_b128 v[194:197], v202 offset:1024
	ds_read_b128 v[198:201], v202 offset:2048
	ds_read_b128 v[202:205], v202 offset:3072
	s_add_u32 s10, s10, s0
	s_addc_u32 s11, s11, 0
	s_mov_b32 m0, s60
	v_lshl_add_u64 v[248:249], s[10:11], 0, v[146:147]
	ds_read_b128 v[206:209], v185 offset:32768
	ds_read_b128 v[210:213], v185 offset:33792
	ds_read_b128 v[214:217], v185 offset:34816
	ds_read_b128 v[218:221], v185 offset:35840
	ds_read_b128 v[222:225], v185 offset:36864
	ds_read_b128 v[226:229], v185 offset:37888
	ds_read_b128 v[230:233], v185 offset:38912
	ds_read_b128 v[234:237], v185 offset:39936
	global_load_lds_dwordx4 v[248:249], off
	v_lshl_add_u64 v[248:249], s[10:11], 0, v[142:143]
	s_mov_b32 m0, s61
	s_nop 0
	global_load_lds_dwordx4 v[248:249], off
	s_waitcnt vmcnt(8)
	s_waitcnt lgkmcnt(0)
	s_barrier
	s_waitcnt lgkmcnt(0)
	v_mfma_f32_16x16x32_bf16 v[126:129], v[130:133], v[206:209], v[126:129]
	v_mfma_f32_16x16x32_bf16 v[122:125], v[156:159], v[206:209], v[122:125]
	v_mfma_f32_16x16x32_bf16 v[110:113], v[130:133], v[214:217], v[110:113]
	v_mfma_f32_16x16x32_bf16 v[106:109], v[156:159], v[214:217], v[106:109]
	v_mfma_f32_16x16x32_bf16 v[94:97], v[130:133], v[222:225], v[94:97]
	v_mfma_f32_16x16x32_bf16 v[90:93], v[156:159], v[222:225], v[90:93]
	v_mfma_f32_16x16x32_bf16 v[78:81], v[130:133], v[230:233], v[78:81]
	v_mfma_f32_16x16x32_bf16 v[74:77], v[156:159], v[230:233], v[74:77]
	v_mfma_f32_16x16x32_bf16 v[126:129], v[134:137], v[210:213], v[126:129]
	v_mfma_f32_16x16x32_bf16 v[122:125], v[186:189], v[210:213], v[122:125]
	v_mfma_f32_16x16x32_bf16 v[110:113], v[134:137], v[218:221], v[110:113]
	v_mfma_f32_16x16x32_bf16 v[106:109], v[186:189], v[218:221], v[106:109]
	v_mfma_f32_16x16x32_bf16 v[94:97], v[134:137], v[226:229], v[94:97]
	v_mfma_f32_16x16x32_bf16 v[90:93], v[186:189], v[226:229], v[90:93]
	v_mfma_f32_16x16x32_bf16 v[78:81], v[134:137], v[234:237], v[78:81]
	v_mfma_f32_16x16x32_bf16 v[74:77], v[186:189], v[234:237], v[74:77]
	v_mfma_f32_16x16x32_bf16 v[118:121], v[190:193], v[206:209], v[118:121]
	v_mfma_f32_16x16x32_bf16 v[114:117], v[198:201], v[206:209], v[114:117]
	v_mfma_f32_16x16x32_bf16 v[102:105], v[190:193], v[214:217], v[102:105]
	v_mfma_f32_16x16x32_bf16 v[98:101], v[198:201], v[214:217], v[98:101]
	v_mfma_f32_16x16x32_bf16 v[86:89], v[190:193], v[222:225], v[86:89]
	v_mfma_f32_16x16x32_bf16 v[82:85], v[198:201], v[222:225], v[82:85]
	v_mfma_f32_16x16x32_bf16 v[70:73], v[190:193], v[230:233], v[70:73]
	v_mfma_f32_16x16x32_bf16 v[66:69], v[198:201], v[230:233], v[66:69]
	v_mfma_f32_16x16x32_bf16 v[118:121], v[194:197], v[210:213], v[118:121]
	v_mfma_f32_16x16x32_bf16 v[114:117], v[202:205], v[210:213], v[114:117]
	v_mfma_f32_16x16x32_bf16 v[102:105], v[194:197], v[218:221], v[102:105]
	v_mfma_f32_16x16x32_bf16 v[98:101], v[202:205], v[218:221], v[98:101]
	v_mfma_f32_16x16x32_bf16 v[86:89], v[194:197], v[226:229], v[86:89]
	v_mfma_f32_16x16x32_bf16 v[82:85], v[202:205], v[226:229], v[82:85]
	v_mfma_f32_16x16x32_bf16 v[70:73], v[194:197], v[234:237], v[70:73]
	v_mfma_f32_16x16x32_bf16 v[66:69], v[202:205], v[234:237], v[66:69]
	s_barrier
	s_add_i32 s10, s66, s33
	v_lshl_add_u64 v[160:161], v[160:161], 0, s[54:55]
	s_mov_b32 m0, s10
	ds_read_b128 v[206:209], v185 offset:49152
	ds_read_b128 v[210:213], v185 offset:50176
	ds_read_b128 v[214:217], v185 offset:51200
	ds_read_b128 v[218:221], v185 offset:52224
	ds_read_b128 v[222:225], v185 offset:53248
	ds_read_b128 v[226:229], v185 offset:54272
	ds_read_b128 v[230:233], v185 offset:55296
	ds_read_b128 v[234:237], v185 offset:56320
	global_load_lds_dwordx4 v[160:161], off
	v_lshl_add_u64 v[160:161], v[238:239], 0, s[54:55]
	s_add_i32 m0, s10, 0x2000
	s_add_i32 s10, s37, s33
	global_load_lds_dwordx4 v[160:161], off
	v_lshl_add_u64 v[160:161], v[240:241], 0, s[54:55]
	s_mov_b32 m0, s10
	s_nop 0
	global_load_lds_dwordx4 v[160:161], off
	v_lshl_add_u64 v[160:161], v[242:243], 0, s[54:55]
	s_add_i32 m0, s10, 0x2000
	s_nop 0
	global_load_lds_dwordx4 v[160:161], off
	v_lshl_add_u64 v[160:161], v[244:245], 0, s[54:55]
	s_mov_b32 m0, s63
	s_nop 0
	global_load_lds_dwordx4 v[160:161], off
	v_lshl_add_u64 v[160:161], v[246:247], 0, s[54:55]
	s_mov_b32 m0, s64
	s_nop 0
	global_load_lds_dwordx4 v[160:161], off
	s_waitcnt vmcnt(8)
	s_waitcnt lgkmcnt(0)
	s_barrier
	s_waitcnt lgkmcnt(0)
	v_mfma_f32_16x16x32_bf16 v[62:65], v[130:133], v[206:209], v[62:65]
	v_mfma_f32_16x16x32_bf16 v[58:61], v[156:159], v[206:209], v[58:61]
	v_mfma_f32_16x16x32_bf16 v[46:49], v[130:133], v[214:217], v[46:49]
	v_mfma_f32_16x16x32_bf16 v[42:45], v[156:159], v[214:217], v[42:45]
	v_mfma_f32_16x16x32_bf16 v[30:33], v[130:133], v[222:225], v[30:33]
	v_mfma_f32_16x16x32_bf16 v[26:29], v[156:159], v[222:225], v[26:29]
	v_mfma_f32_16x16x32_bf16 v[14:17], v[130:133], v[230:233], v[14:17]
	v_mfma_f32_16x16x32_bf16 v[10:13], v[156:159], v[230:233], v[10:13]
	v_mfma_f32_16x16x32_bf16 v[62:65], v[134:137], v[210:213], v[62:65]
	v_mfma_f32_16x16x32_bf16 v[58:61], v[186:189], v[210:213], v[58:61]
	v_mfma_f32_16x16x32_bf16 v[46:49], v[134:137], v[218:221], v[46:49]
	v_mfma_f32_16x16x32_bf16 v[42:45], v[186:189], v[218:221], v[42:45]
	v_mfma_f32_16x16x32_bf16 v[30:33], v[134:137], v[226:229], v[30:33]
	v_mfma_f32_16x16x32_bf16 v[26:29], v[186:189], v[226:229], v[26:29]
	v_mfma_f32_16x16x32_bf16 v[14:17], v[134:137], v[234:237], v[14:17]
	v_mfma_f32_16x16x32_bf16 v[10:13], v[186:189], v[234:237], v[10:13]
	v_mfma_f32_16x16x32_bf16 v[54:57], v[190:193], v[206:209], v[54:57]
	v_mfma_f32_16x16x32_bf16 v[50:53], v[198:201], v[206:209], v[50:53]
	v_mfma_f32_16x16x32_bf16 v[38:41], v[190:193], v[214:217], v[38:41]
	v_mfma_f32_16x16x32_bf16 v[34:37], v[198:201], v[214:217], v[34:37]
	v_mfma_f32_16x16x32_bf16 v[22:25], v[190:193], v[222:225], v[22:25]
	v_mfma_f32_16x16x32_bf16 v[18:21], v[198:201], v[222:225], v[18:21]
	v_mfma_f32_16x16x32_bf16 v[6:9], v[190:193], v[230:233], v[6:9]
	v_mfma_f32_16x16x32_bf16 v[2:5], v[198:201], v[230:233], v[2:5]
	v_mfma_f32_16x16x32_bf16 v[54:57], v[194:197], v[210:213], v[54:57]
	v_mfma_f32_16x16x32_bf16 v[50:53], v[202:205], v[210:213], v[50:53]
	v_mfma_f32_16x16x32_bf16 v[38:41], v[194:197], v[218:221], v[38:41]
	v_mfma_f32_16x16x32_bf16 v[34:37], v[202:205], v[218:221], v[34:37]
	v_mfma_f32_16x16x32_bf16 v[22:25], v[194:197], v[226:229], v[22:25]
	v_mfma_f32_16x16x32_bf16 v[18:21], v[202:205], v[226:229], v[18:21]
	v_mfma_f32_16x16x32_bf16 v[6:9], v[194:197], v[234:237], v[6:9]
	v_mfma_f32_16x16x32_bf16 v[2:5], v[202:205], v[234:237], v[2:5]
	s_barrier
	s_add_u32 s8, s8, 0x100
	s_addc_u32 s9, s9, 0
	s_add_u32 s27, s27, 0x100
	s_addc_u32 s34, s34, 0
	s_cmp_ge_u32 s35, s62
	s_mov_b32 s10, s35
	s_cbranch_scc0 .LBB0_744
	s_and_b64 vcc, exec, s[76:77]
	s_cbranch_vccz .LBB0_747
	s_barrier
